# convert_p rewritten (x4): source pointers fetched once instead of a dependent pointer load per element, 4 row chunks in flight per thread with counted vmcnt
# speedup vs baseline: 1.0419x; 1.0084x over previous
; DI int tid_opaque() { int t = threadIdx.x; asm volatile("" : "+v"(t)); return t; }
; DI u32x2 pack4(float a, float b, float c, float d) { u32x2 r; r.x = pack2(a, b); r.y = pack2(c, d); return r; }
; DI void convert_p(const Params& p, int li, u16* dst) {
;   const long gt = (long)blockIdx.x * NTHR + tid_opaque(), gn = (long)gridDim.x * NTHR;
;   for (long id = gt; id < (long)T_TOK * 64; id += gn) {
;     const long m = id >> 6; const int c4 = (int)(id & 63) * 4;
;     const float* src = (m < TP) ? p.p_prompt + ((long)li * TP + m) * 256 : p.p_sample + ((long)li * (T_TOK - TP) + (m - TP)) * 256;
;     const float4 v = *(const float4*)(src + c4);
;     *(u32x2*)(dst + m * 256 + c4) = pack4(v.x, v.y, v.z, v.w);
;   }
; }
.LBB0_150:
	v_mov_b32_e32 v2, v182
	s_load_dwordx2 s[98:99], s[0:1], 0x10
	s_load_dwordx2 s[100:101], s[0:1], 0x18
	v_add_u32_e32 v0, s80, v182
	v_mov_b32_e32 v8, 0x0
	v_mov_b32_e32 v9, 0xffffc000
	s_waitcnt lgkmcnt(0)
	v_mov_b32_e32 v10, s98
	v_mov_b32_e32 v11, s99
	v_mov_b32_e32 v12, s100
	v_mov_b32_e32 v13, s101
.Lcp0_main:
	v_add_u32_e32 v1, s46, v0
	v_lshl_add_u32 v2, s46, 1, v0
	v_add_u32_e32 v15, s46, v2
	s_nop 0
	v_readfirstlane_b32 s98, v15
	s_nop 3
	s_cmp_lt_u32 s98, 0x500000
	s_cbranch_scc0 .Lcp0_rem
	v_lshrrev_b32_e32 v4, 6, v0
	v_and_b32_e32 v5, 63, v0
	v_cmp_gt_u32_e32 vcc, 0x4000, v4
	v_lshlrev_b32_e32 v14, 9, v4
	v_lshl_add_u32 v14, v5, 3, v14
	v_cndmask_b32_e32 v6, v9, v8, vcc
	v_cndmask_b32_e32 v7, v12, v10, vcc
	v_cndmask_b32_e32 v3, v13, v11, vcc
	v_add_u32_e32 v6, v6, v4
	v_lshlrev_b32_e32 v6, 10, v6
	v_lshl_add_u32 v6, v5, 4, v6
	v_add_co_u32_e32 v6, vcc, v7, v6
	s_nop 1
	v_addc_co_u32_e32 v7, vcc, 0, v3, vcc
	global_load_dwordx4 v[224:227], v[6:7], off
	v_mov_b32_e32 v241, s45
	v_add_co_u32_e32 v240, vcc, s44, v14
	s_nop 1
	v_addc_co_u32_e32 v241, vcc, 0, v241, vcc
	v_lshrrev_b32_e32 v4, 6, v1
	v_and_b32_e32 v5, 63, v1
	v_cmp_gt_u32_e32 vcc, 0x4000, v4
	v_lshlrev_b32_e32 v14, 9, v4
	v_lshl_add_u32 v14, v5, 3, v14
	v_cndmask_b32_e32 v6, v9, v8, vcc
	v_cndmask_b32_e32 v7, v12, v10, vcc
	v_cndmask_b32_e32 v3, v13, v11, vcc
	v_add_u32_e32 v6, v6, v4
	v_lshlrev_b32_e32 v6, 10, v6
	v_lshl_add_u32 v6, v5, 4, v6
	v_add_co_u32_e32 v6, vcc, v7, v6
	s_nop 1
	v_addc_co_u32_e32 v7, vcc, 0, v3, vcc
	global_load_dwordx4 v[228:231], v[6:7], off
	v_mov_b32_e32 v243, s45
	v_add_co_u32_e32 v242, vcc, s44, v14
	s_nop 1
	v_addc_co_u32_e32 v243, vcc, 0, v243, vcc
	v_lshrrev_b32_e32 v4, 6, v2
	v_and_b32_e32 v5, 63, v2
	v_cmp_gt_u32_e32 vcc, 0x4000, v4
	v_lshlrev_b32_e32 v14, 9, v4
	v_lshl_add_u32 v14, v5, 3, v14
	v_cndmask_b32_e32 v6, v9, v8, vcc
	v_cndmask_b32_e32 v7, v12, v10, vcc
	v_cndmask_b32_e32 v3, v13, v11, vcc
	v_add_u32_e32 v6, v6, v4
	v_lshlrev_b32_e32 v6, 10, v6
	v_lshl_add_u32 v6, v5, 4, v6
	v_add_co_u32_e32 v6, vcc, v7, v6
	s_nop 1
	v_addc_co_u32_e32 v7, vcc, 0, v3, vcc
	global_load_dwordx4 v[232:235], v[6:7], off
	v_mov_b32_e32 v245, s45
	v_add_co_u32_e32 v244, vcc, s44, v14
	s_nop 1
	v_addc_co_u32_e32 v245, vcc, 0, v245, vcc
	v_lshrrev_b32_e32 v4, 6, v15
	v_and_b32_e32 v5, 63, v15
	v_cmp_gt_u32_e32 vcc, 0x4000, v4
	v_lshlrev_b32_e32 v14, 9, v4
	v_lshl_add_u32 v14, v5, 3, v14
	v_cndmask_b32_e32 v6, v9, v8, vcc
	v_cndmask_b32_e32 v7, v12, v10, vcc
	v_cndmask_b32_e32 v3, v13, v11, vcc
	v_add_u32_e32 v6, v6, v4
	v_lshlrev_b32_e32 v6, 10, v6
	v_lshl_add_u32 v6, v5, 4, v6
	v_add_co_u32_e32 v6, vcc, v7, v6
	s_nop 1
	v_addc_co_u32_e32 v7, vcc, 0, v3, vcc
	global_load_dwordx4 v[236:239], v[6:7], off
	v_mov_b32_e32 v247, s45
	v_add_co_u32_e32 v246, vcc, s44, v14
	s_nop 1
	v_addc_co_u32_e32 v247, vcc, 0, v247, vcc
	s_waitcnt vmcnt(3)
	v_cvt_pk_bf16_f32 v224, v224, v225
	v_cvt_pk_bf16_f32 v225, v226, v227
	global_store_dwordx2 v[240:241], v[224:225], off
	s_waitcnt vmcnt(3)
	v_cvt_pk_bf16_f32 v228, v228, v229
	v_cvt_pk_bf16_f32 v229, v230, v231
	global_store_dwordx2 v[242:243], v[228:229], off
	s_waitcnt vmcnt(3)
	v_cvt_pk_bf16_f32 v232, v232, v233
	v_cvt_pk_bf16_f32 v233, v234, v235
	global_store_dwordx2 v[244:245], v[232:233], off
	s_waitcnt vmcnt(3)
	v_cvt_pk_bf16_f32 v236, v236, v237
	v_cvt_pk_bf16_f32 v237, v238, v239
	global_store_dwordx2 v[246:247], v[236:237], off
	v_lshl_add_u32 v0, s46, 2, v0
	s_branch .Lcp0_main
.Lcp0_rem:
	v_readfirstlane_b32 s98, v0
	s_nop 3
	s_cmp_lt_u32 s98, 0x500000
	s_cbranch_scc0 .Lcp0_done
	v_lshrrev_b32_e32 v4, 6, v0
	v_and_b32_e32 v5, 63, v0
	v_cmp_gt_u32_e32 vcc, 0x4000, v4
	v_lshlrev_b32_e32 v14, 9, v4
	v_lshl_add_u32 v14, v5, 3, v14
	v_cndmask_b32_e32 v6, v9, v8, vcc
	v_cndmask_b32_e32 v7, v12, v10, vcc
	v_cndmask_b32_e32 v3, v13, v11, vcc
	v_add_u32_e32 v6, v6, v4
	v_lshlrev_b32_e32 v6, 10, v6
	v_lshl_add_u32 v6, v5, 4, v6
	v_add_co_u32_e32 v6, vcc, v7, v6
	s_nop 1
	v_addc_co_u32_e32 v7, vcc, 0, v3, vcc
	global_load_dwordx4 v[224:227], v[6:7], off
	v_mov_b32_e32 v241, s45
	v_add_co_u32_e32 v240, vcc, s44, v14
	s_nop 1
	v_addc_co_u32_e32 v241, vcc, 0, v241, vcc
	s_waitcnt vmcnt(0)
	v_cvt_pk_bf16_f32 v224, v224, v225
	v_cvt_pk_bf16_f32 v225, v226, v227
	global_store_dwordx2 v[240:241], v[224:225], off
	v_add_u32_e32 v0, s46, v0
	s_branch .Lcp0_rem
.Lcp0_done:
.LBB0_153:
	s_or_b64 exec, exec, s[6:7]
	v_or3_b32 v0, v180, v181, v182
	v_cmp_eq_u32_e64 s[86:87], 0, v0
	v_mov_b64_e32 v[128:129], s[44:45]
	s_barrier
	s_and_saveexec_b64 s[8:9], s[86:87]
	s_cbranch_execz .LBB0_163
	buffer_wbl2 sc1
	s_waitcnt vmcnt(0)
	s_load_dwordx2 s[12:13], s[96:97], 0x58
	v_mov_b32_e32 v2, 0
	s_mov_b64 s[14:15], exec
	v_mbcnt_lo_u32_b32 v1, s14, 0
	v_mbcnt_hi_u32_b32 v1, s15, v1
	s_waitcnt lgkmcnt(0)
	global_load_dword v0, v2, s[12:13] offset:40
	v_cmp_eq_u32_e32 vcc, 0, v1
	s_and_saveexec_b64 s[18:19], vcc
	s_cbranch_execz .LBB0_156
	s_bcnt1_i32_b64 s6, s[14:15]
	v_mov_b32_e32 v3, s6
	global_atomic_add v3, v2, v3, s[12:13] offset:32 sc0

; DI int tid_opaque() { int t = threadIdx.x; asm volatile("" : "+v"(t)); return t; }
; DI void convert_p(const Params& p, int li, u16* dst) {
;   const long gt = (long)blockIdx.x * NTHR + tid_opaque(), gn = (long)gridDim.x * NTHR;
;   for (long id = gt; id < (long)T_TOK * 64; id += gn) {
;     const long m = id >> 6; const int c4 = (int)(id & 63) * 4;
;     const float* src = (m < TP) ? p.p_prompt + ((long)li * TP + m) * 256 : p.p_sample + ((long)li * (T_TOK - TP) + (m - TP)) * 256;
.LBB0_298:
	v_mov_b32_e32 v2, v182
	s_load_dwordx2 s[98:99], s[0:1], 0x10
	s_load_dwordx2 s[100:101], s[0:1], 0x18
	v_add_u32_e32 v0, s80, v182
	v_mov_b32_e32 v8, 0x4000
	v_mov_b32_e32 v9, 0xc000
	s_waitcnt lgkmcnt(0)
	v_mov_b32_e32 v10, s98
	v_mov_b32_e32 v11, s99
	v_mov_b32_e32 v12, s100
	v_mov_b32_e32 v13, s101

; DI void gsync(GSync& gs) { cg::this_grid().sync(); }
; DI void run_out_ple(const Params& p, GSync& gs, int li, u16* og, u16* x1b, u16* xb_out, const u16* Wout, unsigned char* smem) {
;     ...
;   convert_p(p, li, (u16*)p.proj);
;   gsync(gs);
.Lcp1_done:
.LBB0_301:
	s_or_b64 exec, exec, s[12:13]
	v_mov_b64_e32 v[128:129], s[44:45]
	s_barrier
	s_and_saveexec_b64 s[12:13], s[86:87]
	s_cbranch_execz .LBB0_311
	buffer_wbl2 sc1
	s_waitcnt vmcnt(0)
	s_load_dwordx2 s[14:15], s[96:97], 0x58
	v_mov_b32_e32 v2, 0
	s_mov_b64 s[16:17], exec
	v_mbcnt_lo_u32_b32 v1, s16, 0
	v_mbcnt_hi_u32_b32 v1, s17, v1
	s_waitcnt lgkmcnt(0)
	global_load_dword v0, v2, s[14:15] offset:40
	v_cmp_eq_u32_e32 vcc, 0, v1
	s_and_saveexec_b64 s[18:19], vcc
	s_cbranch_execz .LBB0_304
	s_bcnt1_i32_b64 s6, s[16:17]
	v_mov_b32_e32 v3, s6
	global_atomic_add v3, v2, v3, s[14:15] offset:32 sc0

; DI int tid_opaque() { int t = threadIdx.x; asm volatile("" : "+v"(t)); return t; }
; DI void convert_p(const Params& p, int li, u16* dst) {
;   const long gt = (long)blockIdx.x * NTHR + tid_opaque(), gn = (long)gridDim.x * NTHR;
;   for (long id = gt; id < (long)T_TOK * 64; id += gn) {
;     const long m = id >> 6; const int c4 = (int)(id & 63) * 4;
;     const float* src = (m < TP) ? p.p_prompt + ((long)li * TP + m) * 256 : p.p_sample + ((long)li * (T_TOK - TP) + (m - TP)) * 256;
.LBB0_507:
	v_mov_b32_e32 v2, v182
	s_load_dwordx2 s[98:99], s[0:1], 0x10
	s_load_dwordx2 s[100:101], s[0:1], 0x18
	v_add_u32_e32 v0, s80, v182
	v_mov_b32_e32 v8, 0x8000
	v_mov_b32_e32 v9, 0x1c000
	s_waitcnt lgkmcnt(0)
	v_mov_b32_e32 v10, s98
	v_mov_b32_e32 v11, s99
	v_mov_b32_e32 v12, s100
	v_mov_b32_e32 v13, s101

; DI int tid_opaque() { int t = threadIdx.x; asm volatile("" : "+v"(t)); return t; }
; DI void convert_p(const Params& p, int li, u16* dst) {
;   const long gt = (long)blockIdx.x * NTHR + tid_opaque(), gn = (long)gridDim.x * NTHR;
;   for (long id = gt; id < (long)T_TOK * 64; id += gn) {
;     const long m = id >> 6; const int c4 = (int)(id & 63) * 4;
;     const float* src = (m < TP) ? p.p_prompt + ((long)li * TP + m) * 256 : p.p_sample + ((long)li * (T_TOK - TP) + (m - TP)) * 256;
.LBB0_660:
	v_mov_b32_e32 v2, v182
	s_load_dwordx2 s[98:99], s[0:1], 0x10
	s_load_dwordx2 s[100:101], s[0:1], 0x18
	v_add_u32_e32 v0, s80, v182
	v_mov_b32_e32 v8, 0xc000
	v_mov_b32_e32 v9, 0x2c000
	s_waitcnt lgkmcnt(0)
	v_mov_b32_e32 v10, s98
	v_mov_b32_e32 v11, s99
	v_mov_b32_e32 v12, s100
	v_mov_b32_e32 v13, s101

; DI u32x2 pack4(float a, float b, float c, float d) { u32x2 r; r.x = pack2(a, b); r.y = pack2(c, d); return r; }
; DI void gsync(GSync& gs) { cg::this_grid().sync(); }
; DI void convert_p(const Params& p, int li, u16* dst) {
;     ...
;   for (long id = gt; id < (long)T_TOK * 64; id += gn) {
;     const long m = id >> 6; const int c4 = (int)(id & 63) * 4;
;     const float* src = (m < TP) ? p.p_prompt + ((long)li * TP + m) * 256 : p.p_sample + ((long)li * (T_TOK - TP) + (m - TP)) * 256;
;     const float4 v = *(const float4*)(src + c4);
;     *(u32x2*)(dst + m * 256 + c4) = pack4(v.x, v.y, v.z, v.w);
;   }
; DI void run_out_ple(const Params& p, GSync& gs, int li, u16* og, u16* x1b, u16* xb_out, const u16* Wout, unsigned char* smem) {
;     ...
;   convert_p(p, li, (u16*)p.proj);
;   gsync(gs);
.Lcp3_done:
.LBB0_663:
	s_or_b64 exec, exec, s[4:5]
	v_mov_b64_e32 v[128:129], s[44:45]
	s_barrier
	s_and_saveexec_b64 s[4:5], s[86:87]
	s_cbranch_execz .LBB0_673
	buffer_wbl2 sc1
	s_waitcnt vmcnt(0)
	s_load_dwordx2 s[10:11], s[96:97], 0x58
	v_mov_b32_e32 v2, 0
	s_mov_b64 s[12:13], exec
	v_mbcnt_lo_u32_b32 v1, s12, 0
	v_mbcnt_hi_u32_b32 v1, s13, v1
	s_waitcnt lgkmcnt(0)
	global_load_dword v0, v2, s[10:11] offset:40
	v_cmp_eq_u32_e32 vcc, 0, v1
	s_and_saveexec_b64 s[14:15], vcc
	s_cbranch_execz .LBB0_666
	s_bcnt1_i32_b64 s3, s[12:13]
	v_mov_b32_e32 v3, s3
	global_atomic_add v3, v2, v3, s[10:11] offset:32 sc0
